# v76 + deferred first-barrier wait: the workgroups that do not block on barrier 1 check its release before arriving at barrier 2 (keeps the arrival counts exact under any skew)
# speedup vs baseline: 1.0011x; 1.0011x over previous
; __device__ __forceinline__ unsigned xb_add(unsigned* p, unsigned v) { return __hip_atomic_fetch_add(p, v, __ATOMIC_RELAXED, __HIP_MEMORY_SCOPE_AGENT); }
; __device__ __forceinline__ void xcd_barrier(const XcdBarrier& b) {
;     asm volatile("s_waitcnt vmcnt(0)" ::: "memory");
;     __syncthreads();
;     if (threadIdx.x == 0) {
;         unsigned* bar = b.bar;
;         __builtin_amdgcn_s_waitcnt(0);
;         unsigned nloc = b.st[0], nx = b.st[1];
;         if (nloc == 0u) { xcd_barrier_complete(bar, b.x, nloc, nx); b.st[0] = nloc; b.st[1] = nx; }
;         const unsigned old = xb_add(&bar[XB_XSUB(b.x)], 1u);
;         const unsigned gen = old / nloc;
.LBB0_190:
	s_mov_b64 s[0:1], exec
	v_readlane_b32 s3, v255, 3
	s_lshl_b32 s3, s3, 8
	v_readlane_b32 s6, v255, 1
	v_mbcnt_lo_u32_b32 v1, s0, 0
	v_readlane_b32 s7, v255, 2
	s_add_u32 s6, s6, s3
	v_mbcnt_hi_u32_b32 v1, s1, v1
	s_addc_u32 s7, s7, 0
	s_cmp_gt_u32 s2, 47
	s_cbranch_scc0 .Lb1d_done
	v_mov_b32_e32 v3, 0x2000
.Lb1d_poll:
	global_load_dword v4, v3, s[6:7] offset:1024 sc1
	s_waitcnt vmcnt(0)
	v_cmp_ne_u32_e32 vcc, 0, v4
	s_cbranch_vccnz .Lb1d_done
	s_sleep 1
	s_branch .Lb1d_poll
.Lb1d_done:
	v_cmp_eq_u32_e32 vcc, 0, v1
	s_and_saveexec_b64 s[8:9], vcc
	s_cbranch_execz .LBB0_192
	s_bcnt1_i32_b64 s0, s[0:1]
	v_mov_b32_e32 v3, 0x1000
	v_mov_b32_e32 v4, s0
	global_atomic_add v3, v3, v4, s[6:7] offset:1024 sc0
